# NSA unit: sliding-window first K/V tile requested before the selected-branch loop into the freed staging registers
# baseline (speedup 1.0000x reference)
; #define NSA_LOADT(kb_, vb_, pitch_) do { int ln_ = lane; asm volatile("" : "+v"(ln_));   \
;         kreg = *(const u32x4*)((kb_) + (unsigned)(ln_ * (pitch_) + wid * 8)); vreg = *(const u32x4*)((vb_) + (unsigned)((16 * (wid & 3) + (ln_ >> 2)) * (pitch_) + (wid >> 2) * 32 + (ln_ & 3) * 8)); } while (0)
; #define NSA_STORET(slot_) do { *(LAS u32x4*)(lds + NL_KS + (slot_) * 8192 + wid * 1024 + lane * 16) = kreg; *(LAS u32x4*)(lds + NL_VS + (slot_) * 8192 + wid * 1024 + lane * 16) = vreg; } while (0)
; __device__ __forceinline__ void nsa_unit(const Ctx& c, int l, int b, int n, int qt) {
;     ...
;     const unsigned long long mq = maskb[tq];
;     unsigned long long uni;
;     { unsigned lo = (unsigned)maskb[lane], hi32 = (unsigned)(maskb[lane] >> 32);
; #pragma unroll
;       for (int o = 1; o < 64; o <<= 1) { lo |= (unsigned)__shfl_xor((int)lo, o); hi32 |= (unsigned)__shfl_xor((int)hi32, o); }
;       uni = ((unsigned long long)(unsigned)__builtin_amdgcn_readfirstlane((int)hi32) << 32) | (unsigned)__builtin_amdgcn_readfirstlane((int)lo); }
;     {
;         NsaSm st; nsa_sm_init(st);
;         const bf16* Kb = H + rowbase * HW + HKV + 256 + n * 64; const bf16* Vb = Kb + 128;
;         unsigned long long rem = uni; int j = __builtin_ctzll(rem); rem &= rem - 1;
;         NSA_LOADT(Kb + (size_t)j * 64 * HW, Vb + (size_t)j * 64 * HW, HW); NSA_STORET(0); __syncthreads();
;     ...
;         const bf16* Kb = H + rowbase * HW + HWIN + n * 64; const bf16* Vb = Kb + 128;
;         const int klast = qt - 8 < 0 ? 0 : qt - 8;
;         int kt = qt;
;         NSA_LOADT(Kb + (size_t)kt * 64 * HW, Vb + (size_t)kt * 64 * HW, HW); NSA_STORET(0); __syncthreads();
.LBB0_1322:
	s_add_i32 s2, 0, 0x18800
	v_lshl_add_u32 v0, v247, 3, s2
	v_lshl_add_u32 v5, v154, 3, s2
	s_waitcnt lgkmcnt(0)
	s_barrier
	ds_read_b64 v[2:3], v0
	ds_read_b64 v[152:153], v5
	v_and_b32_e32 v0, 64, v223
	v_add_u32_e32 v0, 64, v0
	v_xor_b32_e32 v4, 1, v223
	v_cmp_lt_i32_e32 vcc, v4, v0
	s_mul_i32 s16, s16, 0x1c00000
	s_add_u32 s4, s44, s16
	v_cndmask_b32_e32 v4, v223, v4, vcc
	v_lshlrev_b32_e32 v4, 2, v4
	s_waitcnt lgkmcnt(1)
	ds_bpermute_b32 v5, v4, v2
	ds_bpermute_b32 v4, v4, v3
	s_addc_u32 s5, s45, 0
	s_lshl_b32 s6, s17, 1
	s_add_u32 s28, s4, s6
	s_waitcnt lgkmcnt(1)
	v_or_b32_e32 v2, v5, v2
	s_waitcnt lgkmcnt(0)
	v_or_b32_e32 v3, v4, v3
	v_xor_b32_e32 v4, 2, v223
	v_cmp_lt_i32_e32 vcc, v4, v0
	s_addc_u32 s29, s5, 0
	v_mov_b32_e32 v14, v1
	v_cndmask_b32_e32 v4, v223, v4, vcc
	v_lshlrev_b32_e32 v4, 2, v4
	ds_bpermute_b32 v5, v4, v2
	ds_bpermute_b32 v4, v4, v3
	v_mov_b32_e32 v15, v1
	v_mov_b32_e32 v6, v1
	v_mov_b32_e32 v7, v1
	s_waitcnt lgkmcnt(1)
	v_or_b32_e32 v2, v5, v2
	s_waitcnt lgkmcnt(0)
	v_or_b32_e32 v3, v4, v3
	v_xor_b32_e32 v4, 4, v223
	v_cmp_lt_i32_e32 vcc, v4, v0
	v_mov_b32_e32 v8, v1
	v_mov_b32_e32 v9, v1
	v_cndmask_b32_e32 v4, v223, v4, vcc
	v_lshlrev_b32_e32 v4, 2, v4
	ds_bpermute_b32 v5, v4, v2
	ds_bpermute_b32 v4, v4, v3
	v_mov_b32_e32 v10, v1
	v_mov_b32_e32 v11, v1
	v_mov_b32_e32 v12, v1
	s_waitcnt lgkmcnt(1)
	v_or_b32_e32 v2, v5, v2
	s_waitcnt lgkmcnt(0)
	v_or_b32_e32 v3, v4, v3
	v_xor_b32_e32 v4, 8, v223
	v_cmp_lt_i32_e32 vcc, v4, v0
	v_mov_b32_e32 v13, v1
	v_mov_b32_e32 v252, v223
	v_cndmask_b32_e32 v4, v223, v4, vcc
	v_lshlrev_b32_e32 v4, 2, v4
	ds_bpermute_b32 v5, v4, v2
	ds_bpermute_b32 v4, v4, v3
	s_mov_b32 s42, 0
	v_mul_f32_e32 v249, v240, v112
	v_mov_b32_e32 v242, v240
	s_waitcnt lgkmcnt(1)
	v_or_b32_e32 v2, v5, v2
	s_waitcnt lgkmcnt(0)
	v_or_b32_e32 v3, v4, v3
	v_xor_b32_e32 v4, 16, v223
	v_cmp_lt_i32_e32 vcc, v4, v0
	v_mov_b32_e32 v243, v240
	v_mov_b32_e32 v244, v240
	v_cndmask_b32_e32 v4, v223, v4, vcc
	v_lshlrev_b32_e32 v4, 2, v4
	ds_bpermute_b32 v5, v4, v2
	ds_bpermute_b32 v4, v4, v3
	v_mov_b32_e32 v245, v240
	v_mov_b32_e32 v158, 0xc61c4000
	v_mov_b32_e32 v157, 0
	s_waitcnt lgkmcnt(1)
	v_or_b32_e32 v2, v5, v2
	s_waitcnt lgkmcnt(0)
	v_or_b32_e32 v3, v4, v3
	v_xor_b32_e32 v4, 32, v223
	v_cmp_lt_i32_e32 vcc, v4, v0
	s_nop 1
	v_cndmask_b32_e32 v0, v223, v4, vcc
	v_lshlrev_b32_e32 v0, 2, v0
	ds_bpermute_b32 v4, v0, v2
	ds_bpermute_b32 v0, v0, v3
	s_waitcnt lgkmcnt(1)
	v_or_b32_e32 v2, v4, v2
	s_waitcnt lgkmcnt(0)
	v_or_b32_e32 v0, v0, v3
	v_readfirstlane_b32 s2, v2
	v_readfirstlane_b32 s3, v0
	s_flbit_i32_b64 s8, s[2:3]
	s_sub_i32 s8, 63, s8
	s_bitset0_b64 s[2:3], s8
	v_mov_b32_e32 v4, v247
	s_mul_i32 s4, s8, 0x70000
	s_add_u32 s4, s28, s4
	v_mul_lo_u32 v0, v4, s21
	s_addc_u32 s5, s29, 0
	v_add_u32_e32 v0, s1, v0
	v_lshl_add_u64 v[2:3], v[0:1], 1, s[4:5]
	v_lshrrev_b32_e32 v0, 2, v4
	v_add_u32_e32 v0, s22, v0
	v_mul_lo_u32 v0, v0, s21
	v_add_u32_e32 v0, s23, v0
	v_lshlrev_b32_e32 v4, 3, v4
	v_and_or_b32 v0, v4, 24, v0
	v_lshl_add_u64 v[4:5], v[0:1], 1, s[4:5]
	global_load_dwordx4 v[144:147], v[2:3], off offset:1536
	global_load_dwordx4 v[148:151], v[4:5], off offset:1792
	v_mov_b32_e32 v2, v1
	v_mov_b32_e32 v3, v1
	v_mov_b32_e32 v4, v1
	v_mov_b32_e32 v5, v1
	v_mov_b32_e32 v0, v1
	v_mov_b64_e32 v[62:63], v[14:15]
	v_mov_b64_e32 v[78:79], v[14:15]
	v_mov_b64_e32 v[60:61], v[12:13]
	v_mov_b64_e32 v[58:59], v[10:11]
	v_mov_b64_e32 v[56:57], v[8:9]
	v_mov_b64_e32 v[54:55], v[6:7]
	v_mov_b64_e32 v[52:53], v[4:5]
	v_mov_b64_e32 v[50:51], v[2:3]
	v_mov_b64_e32 v[48:49], v[0:1]
	v_mov_b64_e32 v[76:77], v[12:13]
	v_mov_b64_e32 v[74:75], v[10:11]
	v_mov_b64_e32 v[72:73], v[8:9]
	v_mov_b64_e32 v[70:71], v[6:7]
	v_mov_b64_e32 v[68:69], v[4:5]
	v_mov_b64_e32 v[66:67], v[2:3]
	v_mov_b64_e32 v[64:65], v[0:1]
	s_waitcnt vmcnt(1)
	ds_write_b128 v251, v[144:147] offset:1024
	s_waitcnt vmcnt(0)
	ds_write_b128 v251, v[148:151] offset:17408
	v_mov_b32_e32 v4, v247
	s_mul_i32 s4, s46, 0x70000
	s_add_u32 s4, s28, s4
	v_mul_lo_u32 v0, v4, s21
	s_addc_u32 s5, s29, 0
	v_add_u32_e32 v0, s1, v0
	v_lshl_add_u64 v[2:3], v[0:1], 1, s[4:5]
	v_lshrrev_b32_e32 v0, 2, v4
	v_add_u32_e32 v0, s22, v0
	v_mul_lo_u32 v0, v0, s21
	v_add_u32_e32 v0, s23, v0
	v_lshlrev_b32_e32 v4, 3, v4
	v_and_or_b32 v0, v4, 24, v0
	v_lshl_add_u64 v[4:5], v[0:1], 1, s[4:5]
	global_load_dwordx4 v[144:147], v[2:3], off offset:2048
	global_load_dwordx4 v[148:151], v[4:5], off offset:2304
	s_waitcnt lgkmcnt(0)
	s_barrier

; __device__ __forceinline__ float halves_sum(float v) { auto rr = __builtin_amdgcn_permlane32_swap(__float_as_uint(v), __float_as_uint(v), false, false); return __uint_as_float(rr[0]) + __uint_as_float(rr[1]); }
; #define NSA_LOADT(kb_, vb_, pitch_) do { int ln_ = lane; asm volatile("" : "+v"(ln_));   \
;         kreg = *(const u32x4*)((kb_) + (unsigned)(ln_ * (pitch_) + wid * 8)); vreg = *(const u32x4*)((vb_) + (unsigned)((16 * (wid & 3) + (ln_ >> 2)) * (pitch_) + (wid >> 2) * 32 + (ln_ & 3) * 8)); } while (0)
; #define NSA_STORET(slot_) do { *(LAS u32x4*)(lds + NL_KS + (slot_) * 8192 + wid * 1024 + lane * 16) = kreg; *(LAS u32x4*)(lds + NL_VS + (slot_) * 8192 + wid * 1024 + lane * 16) = vreg; } while (0)
; __device__ __forceinline__ void nsa_scores(f32x16& p0, f32x16& p1, float Ap, float slk, int thrp, bool flip) {
; #pragma unroll
;     for (int r = 0; r < 16; ++r) { const int cr = (r & 3) + 8 * (r >> 2);
;         const bool v0 = (cr <= thrp) != flip, v1 = (cr + 32 <= thrp) != flip;
;         p0[r] = v0 ? fmaf(p0[r], C2S, fmaf(slk, (float)cr, Ap)) : SNEG; p1[r] = v1 ? fmaf(p1[r], C2S, fmaf(slk, (float)(cr + 32), Ap)) : SNEG; }
; }
; __device__ __forceinline__ void nsa_unit(const Ctx& c, int l, int b, int n, int qt) {
;     ...
;         const float ltot = halves_sum(st.l); nsa_fold(of0, of1, st.o0, st.o1, ltot > 0.f ? gate1 / ltot : 0.f, wsf, r32, hi);
;     }
;     {
;         NsaSm st; nsa_sm_init(st);
;         const bf16* Kb = H + rowbase * HW + HWIN + n * 64; const bf16* Vb = Kb + 128;
;         const int klast = qt - 8 < 0 ? 0 : qt - 8;
;         int kt = qt;
;         NSA_LOADT(Kb + (size_t)kt * 64 * HW, Vb + (size_t)kt * 64 * HW, HW); NSA_STORET(0); __syncthreads();
.LBB0_1339:
	s_or_b64 exec, exec, s[2:3]
	s_max_i32 s20, s46, 8
	s_waitcnt lgkmcnt(0)
	s_add_i32 s20, s20, -8
	s_mul_i32 s46, s46, 0x70000
	ds_read_b128 v[208:211], v239
	ds_read_b128 v[212:215], v239 offset:32
	ds_read_b128 v[216:219], v239 offset:64
	ds_read_b128 v[220:223], v239 offset:96
	s_add_u32 s2, s28, s46
	s_addc_u32 s3, s29, 0
	v_sub_u32_e32 v0, v154, v156
	v_mov_b32_e32 v14, v1
	v_mov_b32_e32 v15, v1
	v_mov_b32_e32 v2, v1
	v_mov_b32_e32 v3, v1
	v_mov_b32_e32 v4, v1
	v_mov_b32_e32 v5, v1
	v_mov_b32_e32 v6, v1
	v_mov_b32_e32 v7, v1
	v_mov_b32_e32 v8, v1
	v_mov_b32_e32 v9, v1
	v_mov_b32_e32 v10, v1
	v_mov_b32_e32 v11, v1
	v_mov_b32_e32 v12, v1
	v_mov_b32_e32 v13, v1
	v_cmp_gt_i32_e64 s[42:43], 0, v0
	v_cmp_gt_i32_e64 s[44:45], 32, v0
	v_cmp_gt_i32_e64 s[46:47], 1, v0
	v_cmp_gt_i32_e64 s[48:49], 33, v0
	v_cmp_gt_i32_e64 s[50:51], 2, v0
	v_cmp_gt_i32_e64 s[52:53], 34, v0
	v_cmp_gt_i32_e64 s[54:55], 3, v0
	v_cmp_gt_i32_e64 s[56:57], 35, v0
	v_cmp_gt_i32_e64 s[58:59], 8, v0
	v_cmp_gt_i32_e64 s[60:61], 40, v0
	v_cmp_gt_i32_e64 s[62:63], 9, v0
	v_cmp_gt_i32_e64 s[64:65], 41, v0
	v_cmp_gt_i32_e64 s[66:67], 10, v0
	v_cmp_gt_i32_e64 s[68:69], 42, v0
	v_cmp_gt_i32_e64 s[70:71], 11, v0
	v_cmp_gt_i32_e64 s[72:73], 43, v0
	v_cmp_gt_i32_e64 s[74:75], 16, v0
	v_cmp_gt_i32_e64 s[76:77], 48, v0
	v_cmp_gt_i32_e64 s[78:79], 17, v0
	v_cmp_gt_i32_e64 s[80:81], 49, v0
	v_cmp_gt_i32_e64 s[82:83], 18, v0
	v_cmp_gt_i32_e64 s[84:85], 50, v0
	v_cmp_gt_i32_e64 s[86:87], 19, v0
	v_cmp_gt_i32_e64 s[88:89], 51, v0
	v_cmp_gt_i32_e64 s[90:91], 24, v0
	v_cmp_gt_i32_e64 s[92:93], 56, v0
	v_cmp_gt_i32_e64 s[94:95], 25, v0
	v_cmp_gt_i32_e64 s[96:97], 57, v0
	v_cmp_gt_i32_e64 s[36:37], 26, v0
	v_cmp_gt_i32_e64 s[2:3], 58, v0
	v_cmp_gt_i32_e64 s[4:5], 27, v0
	v_cmp_gt_i32_e64 s[6:7], 59, v0
	v_mov_b32_e32 v0, v1
	v_mov_b64_e32 v[94:95], v[14:15]
	v_mov_b64_e32 v[110:111], v[14:15]
	s_mov_b32 s24, 0
	v_mov_b32_e32 v233, 0xc61c4000
	v_mov_b32_e32 v250, 0
	s_sub_i32 s13, 62, s13
	v_mov_b64_e32 v[92:93], v[12:13]
	v_mov_b64_e32 v[90:91], v[10:11]
	v_mov_b64_e32 v[88:89], v[8:9]
	v_mov_b64_e32 v[86:87], v[6:7]
	v_mov_b64_e32 v[84:85], v[4:5]
	v_mov_b64_e32 v[82:83], v[2:3]
	v_mov_b64_e32 v[80:81], v[0:1]
	v_mov_b64_e32 v[108:109], v[12:13]
	v_mov_b64_e32 v[106:107], v[10:11]
	v_mov_b64_e32 v[104:105], v[8:9]
	v_mov_b64_e32 v[102:103], v[6:7]
	v_mov_b64_e32 v[100:101], v[4:5]
	v_mov_b64_e32 v[98:99], v[2:3]
	v_mov_b64_e32 v[96:97], v[0:1]
	s_mov_b32 s25, 0
	s_waitcnt vmcnt(1)
	ds_write_b128 v251, v[144:147] offset:1024
	s_waitcnt vmcnt(0)
	ds_write_b128 v251, v[148:151] offset:17408
	s_waitcnt lgkmcnt(0)
	s_barrier
